# P4 row sums also aggregated across the 4 column waves through LDS (4x fewer atomics); rest as v058
# baseline (speedup 1.0000x reference)
.LBB0_416:
	v_lshl_add_u32 v150, s44, 8, v152
	v_lshl_add_u32 v148, s46, 8, v154
	v_lshlrev_b32_e32 v187, 12, v150
	v_lshlrev_b32_e32 v149, 2, v148
	v_lshl_add_u32 v187, v148, 1, v187
	v_lshlrev_b32_e32 v151, 2, v150
	global_load_dwordx4 v[158:161], v149, s[14:15] offset:0
	global_load_dwordx4 v[162:165], v149, s[14:15] offset:16
	global_load_dwordx4 v[166:169], v149, s[14:15] offset:512
	global_load_dwordx4 v[170:173], v149, s[14:15] offset:528
	s_mov_b32 s98, s18
	s_mov_b32 s99, s19
	s_nop 0
	global_load_dwordx4 v[188:191], v187, s[98:99]
	global_load_dwordx4 v[192:195], v187, s[98:99] offset:256
	global_load_dwordx4 v[174:177], v149, s[80:81] offset:0
	global_load_dwordx4 v[178:181], v149, s[80:81] offset:16
	global_load_dwordx4 v[182:185], v149, s[80:81] offset:512
	global_load_dwordx4 v[144:147], v149, s[80:81] offset:528
	s_add_u32 s98, s18, 0x10000
	s_addc_u32 s99, s19, 0
	s_nop 0
	global_load_dwordx4 v[196:199], v187, s[98:99]
	global_load_dwordx4 v[200:203], v187, s[98:99] offset:256
	s_add_u32 s98, s18, 0x20000
	s_addc_u32 s99, s19, 0
	s_nop 0
	global_load_dwordx4 v[204:207], v187, s[98:99]
	global_load_dwordx4 v[208:211], v187, s[98:99] offset:256
	s_add_u32 s98, s18, 0x30000
	s_addc_u32 s99, s19, 0
	s_nop 0
	global_load_dwordx4 v[212:215], v187, s[98:99]
	global_load_dwordx4 v[216:219], v187, s[98:99] offset:256
	s_add_u32 s98, s18, 0x80000
	s_addc_u32 s99, s19, 0
	s_nop 0
	global_load_dwordx4 v[220:223], v187, s[98:99]
	global_load_dwordx4 v[224:227], v187, s[98:99] offset:256
	s_add_u32 s98, s18, 0x90000
	s_addc_u32 s99, s19, 0
	s_nop 0
	global_load_dwordx4 v[228:231], v187, s[98:99]
	global_load_dwordx4 v[232:235], v187, s[98:99] offset:256
	s_mov_b32 s100, s18
	s_mov_b32 s101, s19
	s_waitcnt vmcnt(15)
	v_and_b32_e32 v237, 0xffff0000, v188
	v_lshlrev_b32_e32 v236, 16, v188
	v_and_b32_e32 v239, 0xffff0000, v189
	v_lshlrev_b32_e32 v238, 16, v189
	v_and_b32_e32 v241, 0xffff0000, v190
	v_lshlrev_b32_e32 v240, 16, v190
	v_and_b32_e32 v243, 0xffff0000, v191
	v_lshlrev_b32_e32 v242, 16, v191
	v_pk_fma_f32 v[124:125], v[236:237], v[158:159], v[124:125]
	v_pk_fma_f32 v[126:127], v[238:239], v[160:161], v[126:127]
	v_pk_fma_f32 v[120:121], v[240:241], v[162:163], v[120:121]
	v_pk_fma_f32 v[122:123], v[242:243], v[164:165], v[122:123]
	v_pk_mul_f32 v[244:245], v[124:125], v[124:125]
	v_pk_fma_f32 v[244:245], v[126:127], v[126:127], v[244:245]
	v_pk_fma_f32 v[244:245], v[120:121], v[120:121], v[244:245]
	v_pk_fma_f32 v[244:245], v[122:123], v[122:123], v[244:245]
	s_waitcnt vmcnt(12)
	v_pk_mul_f32 v[236:237], v[124:125], v[174:175]
	v_pk_mul_f32 v[238:239], v[126:127], v[176:177]
	v_pk_mul_f32 v[240:241], v[120:121], v[178:179]
	v_pk_mul_f32 v[242:243], v[122:123], v[180:181]
	v_cvt_pk_bf16_f32 v188, v236, v237
	v_cvt_pk_bf16_f32 v189, v238, v239
	v_cvt_pk_bf16_f32 v190, v240, v241
	v_cvt_pk_bf16_f32 v191, v242, v243
	s_nop 0
	global_store_dwordx4 v187, v[188:191], s[100:101]
	s_waitcnt vmcnt(15)
	v_and_b32_e32 v237, 0xffff0000, v192
	v_lshlrev_b32_e32 v236, 16, v192
	v_and_b32_e32 v239, 0xffff0000, v193
	v_lshlrev_b32_e32 v238, 16, v193
	v_and_b32_e32 v241, 0xffff0000, v194
	v_lshlrev_b32_e32 v240, 16, v194
	v_and_b32_e32 v243, 0xffff0000, v195
	v_lshlrev_b32_e32 v242, 16, v195
	v_pk_fma_f32 v[116:117], v[236:237], v[166:167], v[116:117]
	v_pk_fma_f32 v[118:119], v[238:239], v[168:169], v[118:119]
	v_pk_fma_f32 v[112:113], v[240:241], v[170:171], v[112:113]
	v_pk_fma_f32 v[114:115], v[242:243], v[172:173], v[114:115]
	v_pk_fma_f32 v[244:245], v[116:117], v[116:117], v[244:245]
	v_pk_fma_f32 v[244:245], v[118:119], v[118:119], v[244:245]
	v_pk_fma_f32 v[244:245], v[112:113], v[112:113], v[244:245]
	v_pk_fma_f32 v[244:245], v[114:115], v[114:115], v[244:245]
	s_waitcnt vmcnt(11)
	v_pk_mul_f32 v[236:237], v[116:117], v[182:183]
	v_pk_mul_f32 v[238:239], v[118:119], v[184:185]
	v_pk_mul_f32 v[240:241], v[112:113], v[144:145]
	v_pk_mul_f32 v[242:243], v[114:115], v[146:147]
	v_cvt_pk_bf16_f32 v192, v236, v237
	v_cvt_pk_bf16_f32 v193, v238, v239
	v_cvt_pk_bf16_f32 v194, v240, v241
	v_cvt_pk_bf16_f32 v195, v242, v243
	s_nop 0
	global_store_dwordx4 v187, v[192:195], s[100:101] offset:256
	v_add_f32_e32 v246, v244, v245
	s_add_u32 s98, s18, 0xa0000
	s_addc_u32 s99, s19, 0
	s_nop 0
	global_load_dwordx4 v[112:115], v187, s[98:99]
	global_load_dwordx4 v[116:119], v187, s[98:99] offset:256
	s_add_u32 s100, s18, 0x10000
	s_addc_u32 s101, s19, 0
	s_waitcnt vmcnt(13)
	v_and_b32_e32 v237, 0xffff0000, v196
	v_lshlrev_b32_e32 v236, 16, v196
	v_and_b32_e32 v239, 0xffff0000, v197
	v_lshlrev_b32_e32 v238, 16, v197
	v_and_b32_e32 v241, 0xffff0000, v198
	v_lshlrev_b32_e32 v240, 16, v198
	v_and_b32_e32 v243, 0xffff0000, v199
	v_lshlrev_b32_e32 v242, 16, v199
	v_pk_fma_f32 v[108:109], v[236:237], v[158:159], v[108:109]
	v_pk_fma_f32 v[110:111], v[238:239], v[160:161], v[110:111]
	v_pk_fma_f32 v[104:105], v[240:241], v[162:163], v[104:105]
	v_pk_fma_f32 v[106:107], v[242:243], v[164:165], v[106:107]
	v_pk_mul_f32 v[244:245], v[108:109], v[108:109]
	v_pk_fma_f32 v[244:245], v[110:111], v[110:111], v[244:245]
	v_pk_fma_f32 v[244:245], v[104:105], v[104:105], v[244:245]
	v_pk_fma_f32 v[244:245], v[106:107], v[106:107], v[244:245]
	v_pk_mul_f32 v[236:237], v[108:109], v[174:175]
	v_pk_mul_f32 v[238:239], v[110:111], v[176:177]
	v_pk_mul_f32 v[240:241], v[104:105], v[178:179]
	v_pk_mul_f32 v[242:243], v[106:107], v[180:181]
	v_cvt_pk_bf16_f32 v196, v236, v237
	v_cvt_pk_bf16_f32 v197, v238, v239
	v_cvt_pk_bf16_f32 v198, v240, v241
	v_cvt_pk_bf16_f32 v199, v242, v243
	s_nop 0
	global_store_dwordx4 v187, v[196:199], s[100:101]
	s_waitcnt vmcnt(13)
	v_and_b32_e32 v237, 0xffff0000, v200
	v_lshlrev_b32_e32 v236, 16, v200
	v_and_b32_e32 v239, 0xffff0000, v201
	v_lshlrev_b32_e32 v238, 16, v201
	v_and_b32_e32 v241, 0xffff0000, v202
	v_lshlrev_b32_e32 v240, 16, v202
	v_and_b32_e32 v243, 0xffff0000, v203
	v_lshlrev_b32_e32 v242, 16, v203
	v_pk_fma_f32 v[100:101], v[236:237], v[166:167], v[100:101]
	v_pk_fma_f32 v[102:103], v[238:239], v[168:169], v[102:103]
	v_pk_fma_f32 v[96:97], v[240:241], v[170:171], v[96:97]
	v_pk_fma_f32 v[98:99], v[242:243], v[172:173], v[98:99]
	v_pk_fma_f32 v[244:245], v[100:101], v[100:101], v[244:245]
	v_pk_fma_f32 v[244:245], v[102:103], v[102:103], v[244:245]
	v_pk_fma_f32 v[244:245], v[96:97], v[96:97], v[244:245]
	v_pk_fma_f32 v[244:245], v[98:99], v[98:99], v[244:245]
	v_pk_mul_f32 v[236:237], v[100:101], v[182:183]
	v_pk_mul_f32 v[238:239], v[102:103], v[184:185]
	v_pk_mul_f32 v[240:241], v[96:97], v[144:145]
	v_pk_mul_f32 v[242:243], v[98:99], v[146:147]
	v_cvt_pk_bf16_f32 v200, v236, v237
	v_cvt_pk_bf16_f32 v201, v238, v239
	v_cvt_pk_bf16_f32 v202, v240, v241
	v_cvt_pk_bf16_f32 v203, v242, v243
	s_nop 0
	global_store_dwordx4 v187, v[200:203], s[100:101] offset:256
	v_add_f32_e32 v247, v244, v245
	s_add_u32 s98, s18, 0xb0000
	s_addc_u32 s99, s19, 0
	s_nop 0
	global_load_dwordx4 v[96:99], v187, s[98:99]
	global_load_dwordx4 v[100:103], v187, s[98:99] offset:256
	s_add_u32 s100, s18, 0x20000
	s_addc_u32 s101, s19, 0
	s_waitcnt vmcnt(15)
	v_and_b32_e32 v237, 0xffff0000, v204
	v_lshlrev_b32_e32 v236, 16, v204
	v_and_b32_e32 v239, 0xffff0000, v205
	v_lshlrev_b32_e32 v238, 16, v205
	v_and_b32_e32 v241, 0xffff0000, v206
	v_lshlrev_b32_e32 v240, 16, v206
	v_and_b32_e32 v243, 0xffff0000, v207
	v_lshlrev_b32_e32 v242, 16, v207
	v_pk_fma_f32 v[92:93], v[236:237], v[158:159], v[92:93]
	v_pk_fma_f32 v[94:95], v[238:239], v[160:161], v[94:95]
	v_pk_fma_f32 v[88:89], v[240:241], v[162:163], v[88:89]
	v_pk_fma_f32 v[90:91], v[242:243], v[164:165], v[90:91]
	v_pk_mul_f32 v[244:245], v[92:93], v[92:93]
	v_pk_fma_f32 v[244:245], v[94:95], v[94:95], v[244:245]
	v_pk_fma_f32 v[244:245], v[88:89], v[88:89], v[244:245]
	v_pk_fma_f32 v[244:245], v[90:91], v[90:91], v[244:245]
	v_pk_mul_f32 v[236:237], v[92:93], v[174:175]
	v_pk_mul_f32 v[238:239], v[94:95], v[176:177]
	v_pk_mul_f32 v[240:241], v[88:89], v[178:179]
	v_pk_mul_f32 v[242:243], v[90:91], v[180:181]
	v_cvt_pk_bf16_f32 v204, v236, v237
	v_cvt_pk_bf16_f32 v205, v238, v239
	v_cvt_pk_bf16_f32 v206, v240, v241
	v_cvt_pk_bf16_f32 v207, v242, v243
	s_nop 0
	global_store_dwordx4 v187, v[204:207], s[100:101]
	s_waitcnt vmcnt(15)
	v_and_b32_e32 v237, 0xffff0000, v208
	v_lshlrev_b32_e32 v236, 16, v208
	v_and_b32_e32 v239, 0xffff0000, v209
	v_lshlrev_b32_e32 v238, 16, v209
	v_and_b32_e32 v241, 0xffff0000, v210
	v_lshlrev_b32_e32 v240, 16, v210
	v_and_b32_e32 v243, 0xffff0000, v211
	v_lshlrev_b32_e32 v242, 16, v211
	v_pk_fma_f32 v[84:85], v[236:237], v[166:167], v[84:85]
	v_pk_fma_f32 v[86:87], v[238:239], v[168:169], v[86:87]
	v_pk_fma_f32 v[80:81], v[240:241], v[170:171], v[80:81]
	v_pk_fma_f32 v[82:83], v[242:243], v[172:173], v[82:83]
	v_pk_fma_f32 v[244:245], v[84:85], v[84:85], v[244:245]
	v_pk_fma_f32 v[244:245], v[86:87], v[86:87], v[244:245]
	v_pk_fma_f32 v[244:245], v[80:81], v[80:81], v[244:245]
	v_pk_fma_f32 v[244:245], v[82:83], v[82:83], v[244:245]
	v_pk_mul_f32 v[236:237], v[84:85], v[182:183]
	v_pk_mul_f32 v[238:239], v[86:87], v[184:185]
	v_pk_mul_f32 v[240:241], v[80:81], v[144:145]
	v_pk_mul_f32 v[242:243], v[82:83], v[146:147]
	v_cvt_pk_bf16_f32 v208, v236, v237
	v_cvt_pk_bf16_f32 v209, v238, v239
	v_cvt_pk_bf16_f32 v210, v240, v241
	v_cvt_pk_bf16_f32 v211, v242, v243
	s_nop 0
	global_store_dwordx4 v187, v[208:211], s[100:101] offset:256
	v_add_f32_e32 v248, v244, v245
	s_add_u32 s100, s18, 0x30000
	s_addc_u32 s101, s19, 0
	s_waitcnt vmcnt(15)
	v_and_b32_e32 v237, 0xffff0000, v212
	v_lshlrev_b32_e32 v236, 16, v212
	v_and_b32_e32 v239, 0xffff0000, v213
	v_lshlrev_b32_e32 v238, 16, v213
	v_and_b32_e32 v241, 0xffff0000, v214
	v_lshlrev_b32_e32 v240, 16, v214
	v_and_b32_e32 v243, 0xffff0000, v215
	v_lshlrev_b32_e32 v242, 16, v215
	v_pk_fma_f32 v[76:77], v[236:237], v[158:159], v[76:77]
	v_pk_fma_f32 v[78:79], v[238:239], v[160:161], v[78:79]
	v_pk_fma_f32 v[72:73], v[240:241], v[162:163], v[72:73]
	v_pk_fma_f32 v[74:75], v[242:243], v[164:165], v[74:75]
	v_pk_mul_f32 v[244:245], v[76:77], v[76:77]
	v_pk_fma_f32 v[244:245], v[78:79], v[78:79], v[244:245]
	v_pk_fma_f32 v[244:245], v[72:73], v[72:73], v[244:245]
	v_pk_fma_f32 v[244:245], v[74:75], v[74:75], v[244:245]
	v_pk_mul_f32 v[236:237], v[76:77], v[174:175]
	v_pk_mul_f32 v[238:239], v[78:79], v[176:177]
	v_pk_mul_f32 v[240:241], v[72:73], v[178:179]
	v_pk_mul_f32 v[242:243], v[74:75], v[180:181]
	v_cvt_pk_bf16_f32 v212, v236, v237
	v_cvt_pk_bf16_f32 v213, v238, v239
	v_cvt_pk_bf16_f32 v214, v240, v241
	v_cvt_pk_bf16_f32 v215, v242, v243
	s_nop 0
	global_store_dwordx4 v187, v[212:215], s[100:101]
	s_waitcnt vmcnt(15)
	v_and_b32_e32 v237, 0xffff0000, v216
	v_lshlrev_b32_e32 v236, 16, v216
	v_and_b32_e32 v239, 0xffff0000, v217
	v_lshlrev_b32_e32 v238, 16, v217
	v_and_b32_e32 v241, 0xffff0000, v218
	v_lshlrev_b32_e32 v240, 16, v218
	v_and_b32_e32 v243, 0xffff0000, v219
	v_lshlrev_b32_e32 v242, 16, v219
	v_pk_fma_f32 v[68:69], v[236:237], v[166:167], v[68:69]
	v_pk_fma_f32 v[70:71], v[238:239], v[168:169], v[70:71]
	v_pk_fma_f32 v[64:65], v[240:241], v[170:171], v[64:65]
	v_pk_fma_f32 v[66:67], v[242:243], v[172:173], v[66:67]
	v_pk_fma_f32 v[244:245], v[68:69], v[68:69], v[244:245]
	v_pk_fma_f32 v[244:245], v[70:71], v[70:71], v[244:245]
	v_pk_fma_f32 v[244:245], v[64:65], v[64:65], v[244:245]
	v_pk_fma_f32 v[244:245], v[66:67], v[66:67], v[244:245]
	v_pk_mul_f32 v[236:237], v[68:69], v[182:183]
	v_pk_mul_f32 v[238:239], v[70:71], v[184:185]
	v_pk_mul_f32 v[240:241], v[64:65], v[144:145]
	v_pk_mul_f32 v[242:243], v[66:67], v[146:147]
	v_cvt_pk_bf16_f32 v216, v236, v237
	v_cvt_pk_bf16_f32 v217, v238, v239
	v_cvt_pk_bf16_f32 v218, v240, v241
	v_cvt_pk_bf16_f32 v219, v242, v243
	s_nop 0
	global_store_dwordx4 v187, v[216:219], s[100:101] offset:256
	v_add_f32_e32 v249, v244, v245
	s_add_u32 s100, s18, 0x80000
	s_addc_u32 s101, s19, 0
	s_waitcnt vmcnt(15)
	v_and_b32_e32 v237, 0xffff0000, v220
	v_lshlrev_b32_e32 v236, 16, v220
	v_and_b32_e32 v239, 0xffff0000, v221
	v_lshlrev_b32_e32 v238, 16, v221
	v_and_b32_e32 v241, 0xffff0000, v222
	v_lshlrev_b32_e32 v240, 16, v222
	v_and_b32_e32 v243, 0xffff0000, v223
	v_lshlrev_b32_e32 v242, 16, v223
	v_pk_fma_f32 v[60:61], v[236:237], v[158:159], v[60:61]
	v_pk_fma_f32 v[62:63], v[238:239], v[160:161], v[62:63]
	v_pk_fma_f32 v[56:57], v[240:241], v[162:163], v[56:57]
	v_pk_fma_f32 v[58:59], v[242:243], v[164:165], v[58:59]
	v_pk_mul_f32 v[244:245], v[60:61], v[60:61]
	v_pk_fma_f32 v[244:245], v[62:63], v[62:63], v[244:245]
	v_pk_fma_f32 v[244:245], v[56:57], v[56:57], v[244:245]
	v_pk_fma_f32 v[244:245], v[58:59], v[58:59], v[244:245]
	v_pk_mul_f32 v[236:237], v[60:61], v[174:175]
	v_pk_mul_f32 v[238:239], v[62:63], v[176:177]
	v_pk_mul_f32 v[240:241], v[56:57], v[178:179]
	v_pk_mul_f32 v[242:243], v[58:59], v[180:181]
	v_cvt_pk_bf16_f32 v220, v236, v237
	v_cvt_pk_bf16_f32 v221, v238, v239
	v_cvt_pk_bf16_f32 v222, v240, v241
	v_cvt_pk_bf16_f32 v223, v242, v243
	s_nop 0
	global_store_dwordx4 v187, v[220:223], s[100:101]
	s_waitcnt vmcnt(15)
	v_and_b32_e32 v237, 0xffff0000, v224
	v_lshlrev_b32_e32 v236, 16, v224
	v_and_b32_e32 v239, 0xffff0000, v225
	v_lshlrev_b32_e32 v238, 16, v225
	v_and_b32_e32 v241, 0xffff0000, v226
	v_lshlrev_b32_e32 v240, 16, v226
	v_and_b32_e32 v243, 0xffff0000, v227
	v_lshlrev_b32_e32 v242, 16, v227
	v_pk_fma_f32 v[52:53], v[236:237], v[166:167], v[52:53]
	v_pk_fma_f32 v[54:55], v[238:239], v[168:169], v[54:55]
	v_pk_fma_f32 v[48:49], v[240:241], v[170:171], v[48:49]
	v_pk_fma_f32 v[50:51], v[242:243], v[172:173], v[50:51]
	v_pk_fma_f32 v[244:245], v[52:53], v[52:53], v[244:245]
	v_pk_fma_f32 v[244:245], v[54:55], v[54:55], v[244:245]
	v_pk_fma_f32 v[244:245], v[48:49], v[48:49], v[244:245]
	v_pk_fma_f32 v[244:245], v[50:51], v[50:51], v[244:245]
	v_pk_mul_f32 v[236:237], v[52:53], v[182:183]
	v_pk_mul_f32 v[238:239], v[54:55], v[184:185]
	v_pk_mul_f32 v[240:241], v[48:49], v[144:145]
	v_pk_mul_f32 v[242:243], v[50:51], v[146:147]
	v_cvt_pk_bf16_f32 v224, v236, v237
	v_cvt_pk_bf16_f32 v225, v238, v239
	v_cvt_pk_bf16_f32 v226, v240, v241
	v_cvt_pk_bf16_f32 v227, v242, v243
	s_nop 0
	global_store_dwordx4 v187, v[224:227], s[100:101] offset:256
	v_add_f32_e32 v250, v244, v245
	s_add_u32 s100, s18, 0x90000
	s_addc_u32 s101, s19, 0
	s_waitcnt vmcnt(15)
	v_and_b32_e32 v237, 0xffff0000, v228
	v_lshlrev_b32_e32 v236, 16, v228
	v_and_b32_e32 v239, 0xffff0000, v229
	v_lshlrev_b32_e32 v238, 16, v229
	v_and_b32_e32 v241, 0xffff0000, v230
	v_lshlrev_b32_e32 v240, 16, v230
	v_and_b32_e32 v243, 0xffff0000, v231
	v_lshlrev_b32_e32 v242, 16, v231
	v_pk_fma_f32 v[44:45], v[236:237], v[158:159], v[44:45]
	v_pk_fma_f32 v[46:47], v[238:239], v[160:161], v[46:47]
	v_pk_fma_f32 v[40:41], v[240:241], v[162:163], v[40:41]
	v_pk_fma_f32 v[42:43], v[242:243], v[164:165], v[42:43]
	v_pk_mul_f32 v[244:245], v[44:45], v[44:45]
	v_pk_fma_f32 v[244:245], v[46:47], v[46:47], v[244:245]
	v_pk_fma_f32 v[244:245], v[40:41], v[40:41], v[244:245]
	v_pk_fma_f32 v[244:245], v[42:43], v[42:43], v[244:245]
	v_pk_mul_f32 v[236:237], v[44:45], v[174:175]
	v_pk_mul_f32 v[238:239], v[46:47], v[176:177]
	v_pk_mul_f32 v[240:241], v[40:41], v[178:179]
	v_pk_mul_f32 v[242:243], v[42:43], v[180:181]
	v_cvt_pk_bf16_f32 v228, v236, v237
	v_cvt_pk_bf16_f32 v229, v238, v239
	v_cvt_pk_bf16_f32 v230, v240, v241
	v_cvt_pk_bf16_f32 v231, v242, v243
	s_nop 0
	global_store_dwordx4 v187, v[228:231], s[100:101]
	s_waitcnt vmcnt(15)
	v_and_b32_e32 v237, 0xffff0000, v232
	v_lshlrev_b32_e32 v236, 16, v232
	v_and_b32_e32 v239, 0xffff0000, v233
	v_lshlrev_b32_e32 v238, 16, v233
	v_and_b32_e32 v241, 0xffff0000, v234
	v_lshlrev_b32_e32 v240, 16, v234
	v_and_b32_e32 v243, 0xffff0000, v235
	v_lshlrev_b32_e32 v242, 16, v235
	v_pk_fma_f32 v[36:37], v[236:237], v[166:167], v[36:37]
	v_pk_fma_f32 v[38:39], v[238:239], v[168:169], v[38:39]
	v_pk_fma_f32 v[32:33], v[240:241], v[170:171], v[32:33]
	v_pk_fma_f32 v[34:35], v[242:243], v[172:173], v[34:35]
	v_pk_fma_f32 v[244:245], v[36:37], v[36:37], v[244:245]
	v_pk_fma_f32 v[244:245], v[38:39], v[38:39], v[244:245]
	v_pk_fma_f32 v[244:245], v[32:33], v[32:33], v[244:245]
	v_pk_fma_f32 v[244:245], v[34:35], v[34:35], v[244:245]
	v_pk_mul_f32 v[236:237], v[36:37], v[182:183]
	v_pk_mul_f32 v[238:239], v[38:39], v[184:185]
	v_pk_mul_f32 v[240:241], v[32:33], v[144:145]
	v_pk_mul_f32 v[242:243], v[34:35], v[146:147]
	v_cvt_pk_bf16_f32 v232, v236, v237
	v_cvt_pk_bf16_f32 v233, v238, v239
	v_cvt_pk_bf16_f32 v234, v240, v241
	v_cvt_pk_bf16_f32 v235, v242, v243
	s_nop 0
	global_store_dwordx4 v187, v[232:235], s[100:101] offset:256
	v_add_f32_e32 v251, v244, v245
	s_add_u32 s100, s18, 0xa0000
	s_addc_u32 s101, s19, 0
	s_waitcnt vmcnt(13)
	v_and_b32_e32 v237, 0xffff0000, v112
	v_lshlrev_b32_e32 v236, 16, v112
	v_and_b32_e32 v239, 0xffff0000, v113
	v_lshlrev_b32_e32 v238, 16, v113
	v_and_b32_e32 v241, 0xffff0000, v114
	v_lshlrev_b32_e32 v240, 16, v114
	v_and_b32_e32 v243, 0xffff0000, v115
	v_lshlrev_b32_e32 v242, 16, v115
	v_pk_fma_f32 v[28:29], v[236:237], v[158:159], v[28:29]
	v_pk_fma_f32 v[30:31], v[238:239], v[160:161], v[30:31]
	v_pk_fma_f32 v[24:25], v[240:241], v[162:163], v[24:25]
	v_pk_fma_f32 v[26:27], v[242:243], v[164:165], v[26:27]
	v_pk_mul_f32 v[244:245], v[28:29], v[28:29]
	v_pk_fma_f32 v[244:245], v[30:31], v[30:31], v[244:245]
	v_pk_fma_f32 v[244:245], v[24:25], v[24:25], v[244:245]
	v_pk_fma_f32 v[244:245], v[26:27], v[26:27], v[244:245]
	v_pk_mul_f32 v[236:237], v[28:29], v[174:175]
	v_pk_mul_f32 v[238:239], v[30:31], v[176:177]
	v_pk_mul_f32 v[240:241], v[24:25], v[178:179]
	v_pk_mul_f32 v[242:243], v[26:27], v[180:181]
	v_cvt_pk_bf16_f32 v112, v236, v237
	v_cvt_pk_bf16_f32 v113, v238, v239
	v_cvt_pk_bf16_f32 v114, v240, v241
	v_cvt_pk_bf16_f32 v115, v242, v243
	s_nop 0
	global_store_dwordx4 v187, v[112:115], s[100:101]
	s_waitcnt vmcnt(13)
	v_and_b32_e32 v237, 0xffff0000, v116
	v_lshlrev_b32_e32 v236, 16, v116
	v_and_b32_e32 v239, 0xffff0000, v117
	v_lshlrev_b32_e32 v238, 16, v117
	v_and_b32_e32 v241, 0xffff0000, v118
	v_lshlrev_b32_e32 v240, 16, v118
	v_and_b32_e32 v243, 0xffff0000, v119
	v_lshlrev_b32_e32 v242, 16, v119
	v_pk_fma_f32 v[20:21], v[236:237], v[166:167], v[20:21]
	v_pk_fma_f32 v[22:23], v[238:239], v[168:169], v[22:23]
	v_pk_fma_f32 v[16:17], v[240:241], v[170:171], v[16:17]
	v_pk_fma_f32 v[18:19], v[242:243], v[172:173], v[18:19]
	v_pk_fma_f32 v[244:245], v[20:21], v[20:21], v[244:245]
	v_pk_fma_f32 v[244:245], v[22:23], v[22:23], v[244:245]
	v_pk_fma_f32 v[244:245], v[16:17], v[16:17], v[244:245]
	v_pk_fma_f32 v[244:245], v[18:19], v[18:19], v[244:245]
	v_pk_mul_f32 v[236:237], v[20:21], v[182:183]
	v_pk_mul_f32 v[238:239], v[22:23], v[184:185]
	v_pk_mul_f32 v[240:241], v[16:17], v[144:145]
	v_pk_mul_f32 v[242:243], v[18:19], v[146:147]
	v_cvt_pk_bf16_f32 v116, v236, v237
	v_cvt_pk_bf16_f32 v117, v238, v239
	v_cvt_pk_bf16_f32 v118, v240, v241
	v_cvt_pk_bf16_f32 v119, v242, v243
	s_nop 0
	global_store_dwordx4 v187, v[116:119], s[100:101] offset:256
	v_add_f32_e32 v252, v244, v245
	s_add_u32 s100, s18, 0xb0000
	s_addc_u32 s101, s19, 0
	s_waitcnt vmcnt(11)
	v_and_b32_e32 v237, 0xffff0000, v96
	v_lshlrev_b32_e32 v236, 16, v96
	v_and_b32_e32 v239, 0xffff0000, v97
	v_lshlrev_b32_e32 v238, 16, v97
	v_and_b32_e32 v241, 0xffff0000, v98
	v_lshlrev_b32_e32 v240, 16, v98
	v_and_b32_e32 v243, 0xffff0000, v99
	v_lshlrev_b32_e32 v242, 16, v99
	v_pk_fma_f32 v[12:13], v[236:237], v[158:159], v[12:13]
	v_pk_fma_f32 v[14:15], v[238:239], v[160:161], v[14:15]
	v_pk_fma_f32 v[8:9], v[240:241], v[162:163], v[8:9]
	v_pk_fma_f32 v[10:11], v[242:243], v[164:165], v[10:11]
	v_pk_mul_f32 v[244:245], v[12:13], v[12:13]
	v_pk_fma_f32 v[244:245], v[14:15], v[14:15], v[244:245]
	v_pk_fma_f32 v[244:245], v[8:9], v[8:9], v[244:245]
	v_pk_fma_f32 v[244:245], v[10:11], v[10:11], v[244:245]
	v_pk_mul_f32 v[236:237], v[12:13], v[174:175]
	v_pk_mul_f32 v[238:239], v[14:15], v[176:177]
	v_pk_mul_f32 v[240:241], v[8:9], v[178:179]
	v_pk_mul_f32 v[242:243], v[10:11], v[180:181]
	v_cvt_pk_bf16_f32 v96, v236, v237
	v_cvt_pk_bf16_f32 v97, v238, v239
	v_cvt_pk_bf16_f32 v98, v240, v241
	v_cvt_pk_bf16_f32 v99, v242, v243
	s_nop 0
	global_store_dwordx4 v187, v[96:99], s[100:101]
	s_waitcnt vmcnt(11)
	v_and_b32_e32 v237, 0xffff0000, v100
	v_lshlrev_b32_e32 v236, 16, v100
	v_and_b32_e32 v239, 0xffff0000, v101
	v_lshlrev_b32_e32 v238, 16, v101
	v_and_b32_e32 v241, 0xffff0000, v102
	v_lshlrev_b32_e32 v240, 16, v102
	v_and_b32_e32 v243, 0xffff0000, v103
	v_lshlrev_b32_e32 v242, 16, v103
	v_pk_fma_f32 v[4:5], v[236:237], v[166:167], v[4:5]
	v_pk_fma_f32 v[6:7], v[238:239], v[168:169], v[6:7]
	v_pk_fma_f32 v[0:1], v[240:241], v[170:171], v[0:1]
	v_pk_fma_f32 v[2:3], v[242:243], v[172:173], v[2:3]
	v_pk_fma_f32 v[244:245], v[4:5], v[4:5], v[244:245]
	v_pk_fma_f32 v[244:245], v[6:7], v[6:7], v[244:245]
	v_pk_fma_f32 v[244:245], v[0:1], v[0:1], v[244:245]
	v_pk_fma_f32 v[244:245], v[2:3], v[2:3], v[244:245]
	v_pk_mul_f32 v[236:237], v[4:5], v[182:183]
	v_pk_mul_f32 v[238:239], v[6:7], v[184:185]
	v_pk_mul_f32 v[240:241], v[0:1], v[144:145]
	v_pk_mul_f32 v[242:243], v[2:3], v[146:147]
	v_cvt_pk_bf16_f32 v100, v236, v237
	v_cvt_pk_bf16_f32 v101, v238, v239
	v_cvt_pk_bf16_f32 v102, v240, v241
	v_cvt_pk_bf16_f32 v103, v242, v243
	s_nop 0
	global_store_dwordx4 v187, v[100:103], s[100:101] offset:256
	v_add_f32_e32 v253, v244, v245
	v_xor_b32_e32 v236, 16, v186
	v_xor_b32_e32 v237, 32, v186
	v_lshlrev_b32_e32 v236, 2, v236
	v_lshlrev_b32_e32 v237, 2, v237
	ds_bpermute_b32 v120, v236, v246
	ds_bpermute_b32 v121, v236, v247
	ds_bpermute_b32 v122, v236, v248
	ds_bpermute_b32 v123, v236, v249
	ds_bpermute_b32 v124, v236, v250
	ds_bpermute_b32 v125, v236, v251
	ds_bpermute_b32 v126, v236, v252
	ds_bpermute_b32 v127, v236, v253
	s_waitcnt lgkmcnt(7)
	v_add_f32_e32 v246, v246, v120
	s_waitcnt lgkmcnt(6)
	v_add_f32_e32 v247, v247, v121
	s_waitcnt lgkmcnt(5)
	v_add_f32_e32 v248, v248, v122
	s_waitcnt lgkmcnt(4)
	v_add_f32_e32 v249, v249, v123
	s_waitcnt lgkmcnt(3)
	v_add_f32_e32 v250, v250, v124
	s_waitcnt lgkmcnt(2)
	v_add_f32_e32 v251, v251, v125
	s_waitcnt lgkmcnt(1)
	v_add_f32_e32 v252, v252, v126
	s_waitcnt lgkmcnt(0)
	v_add_f32_e32 v253, v253, v127
	ds_bpermute_b32 v120, v237, v246
	ds_bpermute_b32 v121, v237, v247
	ds_bpermute_b32 v122, v237, v248
	ds_bpermute_b32 v123, v237, v249
	ds_bpermute_b32 v124, v237, v250
	ds_bpermute_b32 v125, v237, v251
	ds_bpermute_b32 v126, v237, v252
	ds_bpermute_b32 v127, v237, v253
	s_waitcnt lgkmcnt(7)
	v_add_f32_e32 v246, v246, v120
	s_waitcnt lgkmcnt(6)
	v_add_f32_e32 v247, v247, v121
	s_waitcnt lgkmcnt(5)
	v_add_f32_e32 v248, v248, v122
	s_waitcnt lgkmcnt(4)
	v_add_f32_e32 v249, v249, v123
	s_waitcnt lgkmcnt(3)
	v_add_f32_e32 v250, v250, v124
	s_waitcnt lgkmcnt(2)
	v_add_f32_e32 v251, v251, v125
	s_waitcnt lgkmcnt(1)
	v_add_f32_e32 v252, v252, v126
	s_waitcnt lgkmcnt(0)
	v_add_f32_e32 v253, v253, v127
	v_readlane_b32 s98, v254, 6
	s_nop 3
	s_lshl_b32 s99, s98, 3
	s_and_b32 s100, s98, 0x100
	s_lshl_b32 s100, s100, 3
	s_bfe_u32 s101, s98, 0x20006
	s_lshl_b32 s98, s101, 7
	s_add_i32 s100, s100, s98
	v_and_b32_e32 v236, 15, v186
	v_lshlrev_b32_e32 v236, 2, v236
	v_add_u32_e32 v236, 0x20800, v236
	v_add_u32_e32 v237, s100, v236
	v_add_u32_e32 v236, s99, v236
	s_and_saveexec_b64 s[44:45], s[4:5]
	ds_write_b32 v236, v246 offset:0
	ds_write_b32 v236, v247 offset:64
	ds_write_b32 v236, v248 offset:128
	ds_write_b32 v236, v249 offset:192
	ds_write_b32 v236, v250 offset:256
	ds_write_b32 v236, v251 offset:320
	ds_write_b32 v236, v252 offset:384
	ds_write_b32 v236, v253 offset:448
	s_waitcnt lgkmcnt(0)
	s_or_b64 exec, exec, s[44:45]
	s_barrier
	s_and_saveexec_b64 s[44:45], s[4:5]
	ds_read_b32 v120, v237 offset:0
	ds_read_b32 v121, v237 offset:512
	ds_read_b32 v122, v237 offset:1024
	ds_read_b32 v123, v237 offset:1536
	ds_read_b32 v124, v237 offset:64
	ds_read_b32 v125, v237 offset:576
	ds_read_b32 v126, v237 offset:1088
	ds_read_b32 v127, v237 offset:1600
	s_and_b32 s99, s101, 1
	s_lshl_b32 s99, s99, 7
	s_lshr_b32 s100, s101, 1
	s_lshl_b32 s100, s100, 9
	s_add_i32 s99, s99, s100
	v_add_u32_e32 v236, s99, v151
	s_waitcnt lgkmcnt(0)
	v_add_f32_e32 v120, v120, v121
	v_add_f32_e32 v122, v122, v123
	v_add_f32_e32 v120, v120, v122
	global_atomic_add_f32 v236, v120, s[12:13]
	v_add_f32_e32 v124, v124, v125
	v_add_f32_e32 v126, v126, v127
	v_add_f32_e32 v124, v124, v126
	global_atomic_add_f32 v236, v124, s[12:13] offset:64
